# GQA loop: S3 V-fragment reads issued progressively behind the row-sum groups (like S1), missing lgkmcnt waits added for the reordered V reads in S2/S4; diff K-tile row-group layout; on top of v1
# baseline (speedup 1.0000x reference)
;   #define MF(k,q,c) __builtin_amdgcn_mfma_f32_32x32x16_bf16(k,q,c,0,0,0)
;   #define X4(P,B) do{ P[B]=__builtin_amdgcn_exp2f(P[B]); P[B+1]=__builtin_amdgcn_exp2f(P[B+1]); P[B+2]=__builtin_amdgcn_exp2f(P[B+2]); P[B+3]=__builtin_amdgcn_exp2f(P[B+3]); asm volatile("":"+v"(P)); SBAR(); }while(0)
;   #define SP4(SUM,P,B,PW,H) do{ SUM+=P[B]; SUM+=P[B+1]; SUM+=P[B+2]; SUM+=P[B+3]; asm volatile("":"+v"(SUM)); PW[(H)*2]=cvtpk_s(P[B],P[B+1]); PW[(H)*2+1]=cvtpk_s(P[B+2],P[B+3]); asm volatile("":"+v"(PW)); SBAR(); }while(0)
;     #define VLD() do{ _Pragma("unroll") for(int i=0;i<8;++i){ vlo[i]=vtr(vq+((i>>2)*4096+(i&3)*1024)); vhi[i]=vtr(vq+((i>>2)*4096+(i&3)*1024+512)); } }while(0)
;     #define PVA(ks,d0) oa[d0]=MF(__builtin_bit_cast(bf16x8,pa[ks]),VF((ks)+4*(d0)),oa[d0])
; __device__ __forceinline__ void attn_unit2(const bf16*Qu,int qp,const bf16*__restrict__ Kh,int kp,const bf16*__restrict__ Vh,int vp,bf16*Ou,int op,int NT,char*shm,int tid_in){
;     ...
;     b0=MF(kf[0],qb[0],z16); SP4(sa,a0,0,pa[0],0);  b1=MF(kf[1],qb[0],z16); SP4(sa,a0,4,pa[0],1);
;     b0=MF(kf[2],qb[1],b0);  SP4(sa,a0,8,pa[1],0);  b1=MF(kf[3],qb[1],b1);  SP4(sa,a0,12,pa[1],1);
;     b0=MF(kf[4],qb[2],b0);  SP4(sa,a1,0,pa[2],0);  b1=MF(kf[5],qb[2],b1);  SP4(sa,a1,4,pa[2],1);
;     b0=MF(kf[6],qb[3],b0);  SP4(sa,a1,8,pa[3],0);  b1=MF(kf[7],qb[3],b1);  SP4(sa,a1,12,pa[3],1);
;     la+=sa;
;     VLD(); if(nx) kload8(kf,kp0+sl_n1);
;     ...
;     PVA(0,0); X4(b0,0); PVA(0,1); X4(b0,4); PVA(1,0); X4(b0,8); PVA(1,1); X4(b0,12);
;     PVA(2,0); X4(b1,0); PVA(2,1); X4(b1,4); PVA(3,0); X4(b1,8); PVA(3,1); X4(b1,12);
.LBB0_896:
	s_add_i32 s13, s13, 1
	v_add_u32_e32 v240, s14, v0
	v_mfma_f32_32x32x16_bf16 v[114:129], v[206:209], v[150:153], 0
	v_add_f32_e32 v232, 0, v82
	v_cvt_pk_bf16_f32 v158, v82, v83
	v_add_f32_e32 v232, v83, v232
	v_add_f32_e32 v232, v84, v232
	v_cvt_pk_bf16_f32 v159, v84, v85
	v_add_f32_e32 v232, v85, v232
	ds_read_b64_tr_b16 v[82:83], v240 offset:36864
	ds_read_b64_tr_b16 v[84:85], v240 offset:37376
	v_mfma_f32_32x32x16_bf16 v[98:113], v[210:213], v[150:153], 0
	v_add_f32_e32 v232, v86, v232
	v_cvt_pk_bf16_f32 v160, v86, v87
	v_add_f32_e32 v232, v87, v232
	v_add_f32_e32 v232, v88, v232
	v_cvt_pk_bf16_f32 v161, v88, v89
	v_add_f32_e32 v232, v89, v232
	ds_read_b64_tr_b16 v[86:87], v240 offset:37888
	ds_read_b64_tr_b16 v[88:89], v240 offset:38400
	v_mfma_f32_32x32x16_bf16 v[114:129], v[202:205], v[146:149], v[114:129]
	v_add_f32_e32 v232, v90, v232
	v_cvt_pk_bf16_f32 v154, v90, v91
	v_add_f32_e32 v232, v91, v232
	v_add_f32_e32 v232, v92, v232
	v_cvt_pk_bf16_f32 v155, v92, v93
	v_add_f32_e32 v232, v93, v232
	ds_read_b64_tr_b16 v[90:91], v240 offset:38912
	ds_read_b64_tr_b16 v[92:93], v240 offset:39424
	v_mfma_f32_32x32x16_bf16 v[98:113], v[198:201], v[146:149], v[98:113]
	v_add_f32_e32 v232, v94, v232
	v_cvt_pk_bf16_f32 v156, v94, v95
	v_add_f32_e32 v232, v95, v232
	v_add_f32_e32 v232, v96, v232
	v_cvt_pk_bf16_f32 v157, v96, v97
	v_add_f32_e32 v232, v97, v232
	ds_read_b64_tr_b16 v[94:95], v240 offset:39936
	ds_read_b64_tr_b16 v[96:97], v240 offset:40448
	v_mfma_f32_32x32x16_bf16 v[114:129], v[222:225], v[142:145], v[114:129]
	v_add_f32_e32 v232, v66, v232
	v_cvt_pk_bf16_f32 v138, v66, v67
	v_add_f32_e32 v232, v67, v232
	v_add_f32_e32 v232, v68, v232
	v_cvt_pk_bf16_f32 v139, v68, v69
	v_add_f32_e32 v232, v69, v232
	ds_read_b64_tr_b16 v[66:67], v240 offset:32768
	ds_read_b64_tr_b16 v[68:69], v240 offset:33280
	v_mfma_f32_32x32x16_bf16 v[98:113], v[218:221], v[142:145], v[98:113]
	v_add_f32_e32 v232, v70, v232
	v_cvt_pk_bf16_f32 v140, v70, v71
	v_add_f32_e32 v232, v71, v232
	v_add_f32_e32 v232, v72, v232
	v_cvt_pk_bf16_f32 v141, v72, v73
	v_add_f32_e32 v232, v73, v232
	ds_read_b64_tr_b16 v[70:71], v240 offset:33792
	ds_read_b64_tr_b16 v[72:73], v240 offset:34304
	v_mfma_f32_32x32x16_bf16 v[114:129], v[214:217], v[130:133], v[114:129]
	v_add_f32_e32 v232, v74, v232
	v_cvt_pk_bf16_f32 v134, v74, v75
	v_add_f32_e32 v232, v75, v232
	v_add_f32_e32 v232, v76, v232
	v_cvt_pk_bf16_f32 v135, v76, v77
	v_add_f32_e32 v232, v77, v232
	ds_read_b64_tr_b16 v[74:75], v240 offset:34816
	ds_read_b64_tr_b16 v[76:77], v240 offset:35328
	v_mfma_f32_32x32x16_bf16 v[98:113], v[194:197], v[130:133], v[98:113]
	v_add_f32_e32 v232, v78, v232
	v_cvt_pk_bf16_f32 v136, v78, v79
	v_add_f32_e32 v232, v79, v232
	v_add_f32_e32 v232, v80, v232
	v_cvt_pk_bf16_f32 v137, v80, v81
	v_add_f32_e32 v232, v81, v232
	ds_read_b64_tr_b16 v[78:79], v240 offset:35840
	ds_read_b64_tr_b16 v[80:81], v240 offset:36352
	v_add_u32_e32 v162, s16, v241
	ds_read_b128 v[206:209], v162
	ds_read_b128 v[210:213], v162 offset:512
	ds_read_b128 v[202:205], v162 offset:2048
	ds_read_b128 v[198:201], v162 offset:2560
	ds_read_b128 v[222:225], v162 offset:4096
	ds_read_b128 v[218:221], v162 offset:4608
	ds_read_b128 v[214:217], v162 offset:6144
	ds_read_b128 v[194:197], v162 offset:6656
	s_waitcnt lgkmcnt(14)
	v_mfma_f32_32x32x16_bf16 v[2:17], v[158:161], v[66:69], v[2:17]
	v_exp_f32_e32 v114, v114
	v_exp_f32_e32 v115, v115
	v_exp_f32_e32 v116, v116
	v_exp_f32_e32 v117, v117
	s_waitcnt lgkmcnt(14)
	v_mfma_f32_32x32x16_bf16 v[18:33], v[158:161], v[82:85], v[18:33]
	v_exp_f32_e32 v118, v118
	v_exp_f32_e32 v119, v119
	v_exp_f32_e32 v120, v120
	v_exp_f32_e32 v121, v121
	s_waitcnt lgkmcnt(12)
	v_mfma_f32_32x32x16_bf16 v[2:17], v[154:157], v[70:73], v[2:17]
	v_exp_f32_e32 v122, v122
	v_exp_f32_e32 v123, v123
	v_exp_f32_e32 v124, v124
	v_exp_f32_e32 v125, v125
	s_waitcnt lgkmcnt(12)
	v_mfma_f32_32x32x16_bf16 v[18:33], v[154:157], v[86:89], v[18:33]
	v_exp_f32_e32 v126, v126
	v_exp_f32_e32 v127, v127
	v_exp_f32_e32 v128, v128
	v_exp_f32_e32 v129, v129
	s_waitcnt lgkmcnt(10)
	v_mfma_f32_32x32x16_bf16 v[2:17], v[138:141], v[74:77], v[2:17]
	v_exp_f32_e32 v98, v98
	v_exp_f32_e32 v99, v99
	v_exp_f32_e32 v100, v100
	v_exp_f32_e32 v101, v101
	s_waitcnt lgkmcnt(10)
	v_mfma_f32_32x32x16_bf16 v[18:33], v[138:141], v[90:93], v[18:33]
	v_exp_f32_e32 v102, v102
	v_exp_f32_e32 v103, v103
	v_exp_f32_e32 v104, v104
	v_exp_f32_e32 v105, v105
	s_waitcnt lgkmcnt(8)
	v_mfma_f32_32x32x16_bf16 v[2:17], v[134:137], v[78:81], v[2:17]
	v_exp_f32_e32 v106, v106
	v_exp_f32_e32 v107, v107
	v_exp_f32_e32 v108, v108
	v_exp_f32_e32 v109, v109
	s_waitcnt lgkmcnt(8)
	v_mfma_f32_32x32x16_bf16 v[18:33], v[134:137], v[94:97], v[18:33]
	v_exp_f32_e32 v110, v110
	v_exp_f32_e32 v111, v111
	v_exp_f32_e32 v112, v112
	v_exp_f32_e32 v113, v113
	s_waitcnt lgkmcnt(7)
; #define SBAR() __builtin_amdgcn_sched_barrier(0)
;   #define MF(k,q,c) __builtin_amdgcn_mfma_f32_32x32x16_bf16(k,q,c,0,0,0)
;   #define X4(P,B) do{ P[B]=__builtin_amdgcn_exp2f(P[B]); P[B+1]=__builtin_amdgcn_exp2f(P[B+1]); P[B+2]=__builtin_amdgcn_exp2f(P[B+2]); P[B+3]=__builtin_amdgcn_exp2f(P[B+3]); asm volatile("":"+v"(P)); SBAR(); }while(0)
;   #define SP4(SUM,P,B,PW,H) do{ SUM+=P[B]; SUM+=P[B+1]; SUM+=P[B+2]; SUM+=P[B+3]; asm volatile("":"+v"(SUM)); PW[(H)*2]=cvtpk_s(P[B],P[B+1]); PW[(H)*2+1]=cvtpk_s(P[B+2],P[B+3]); asm volatile("":"+v"(PW)); SBAR(); }while(0)
;     #define VLD() do{ _Pragma("unroll") for(int i=0;i<8;++i){ vlo[i]=vtr(vq+((i>>2)*4096+(i&3)*1024)); vhi[i]=vtr(vq+((i>>2)*4096+(i&3)*1024+512)); } }while(0)
;     #define PVB(ks,d0) ob[d0]=MF(__builtin_bit_cast(bf16x8,pb[ks]),VF((ks)+4*(d0)),ob[d0])
; __device__ __forceinline__ void attn_unit2(const bf16*Qu,int qp,const bf16*__restrict__ Kh,int kp,const bf16*__restrict__ Vh,int vp,bf16*Ou,int op,int NT,char*shm,int tid_in){
;     ...
;     if(nx){ a0=MF(kf[0],qa[0],z16); } SP4(sb,b0,0,pb[0],0);  if(nx){ a1=MF(kf[1],qa[0],z16); } SP4(sb,b0,4,pb[0],1);
;     if(nx){ a0=MF(kf[2],qa[1],a0); }  SP4(sb,b0,8,pb[1],0);  if(nx){ a1=MF(kf[3],qa[1],a1); }  SP4(sb,b0,12,pb[1],1);
;     if(nx){ a0=MF(kf[4],qa[2],a0); }  SP4(sb,b1,0,pb[2],0);  if(nx){ a1=MF(kf[5],qa[2],a1); }  SP4(sb,b1,4,pb[2],1);
;     if(nx){ a0=MF(kf[6],qa[3],a0); }  SP4(sb,b1,8,pb[3],0);  if(nx){ a1=MF(kf[7],qa[3],a1); }  SP4(sb,b1,12,pb[3],1);
;     lb+=sb;
;     VLD(); SBAR();
;     PVB(0,0); if(nx) X4(a0,0); PVB(0,1); if(nx) X4(a0,4); PVB(1,0); if(nx) X4(a0,8); PVB(1,1); if(nx) X4(a0,12);
;     PVB(2,0); if(nx) X4(a1,0); PVB(2,1); if(nx) X4(a1,4); PVB(3,0); if(nx) X4(a1,8); PVB(3,1); if(nx) X4(a1,12);
;     SBAR();
;     ...
;     sl_cur=(sl_cur==3*SLOTB)?0:sl_cur+SLOTB; sl_n1=(sl_n1==3*SLOTB)?0:sl_n1+SLOTB; sl_n3=(sl_n3==3*SLOTB)?0:sl_n3+SLOTB;
	v_mfma_f32_32x32x16_bf16 v[82:97], v[206:209], v[170:173], 0
	v_add_f32_e32 v233, 0, v114
	v_cvt_pk_bf16_f32 v162, v114, v115
	v_add_f32_e32 v233, v115, v233
	v_add_f32_e32 v233, v116, v233
	v_cvt_pk_bf16_f32 v163, v116, v117
	v_add_f32_e32 v233, v117, v233
	ds_read_b64_tr_b16 v[114:115], v240 offset:36864
	ds_read_b64_tr_b16 v[116:117], v240 offset:37376
	s_waitcnt lgkmcnt(8)
	v_mfma_f32_32x32x16_bf16 v[66:81], v[210:213], v[170:173], 0
	v_add_f32_e32 v233, v118, v233
	v_cvt_pk_bf16_f32 v164, v118, v119
	v_add_f32_e32 v233, v119, v233
	v_add_f32_e32 v233, v120, v233
	v_cvt_pk_bf16_f32 v165, v120, v121
	v_add_f32_e32 v233, v121, v233
	ds_read_b64_tr_b16 v[118:119], v240 offset:37888
	ds_read_b64_tr_b16 v[120:121], v240 offset:38400
	s_waitcnt lgkmcnt(9)
	v_mfma_f32_32x32x16_bf16 v[82:97], v[202:205], v[174:177], v[82:97]
	v_add_f32_e32 v233, v122, v233
	v_cvt_pk_bf16_f32 v166, v122, v123
	v_add_f32_e32 v233, v123, v233
	v_add_f32_e32 v233, v124, v233
	v_cvt_pk_bf16_f32 v167, v124, v125
	v_add_f32_e32 v233, v125, v233
	ds_read_b64_tr_b16 v[122:123], v240 offset:38912
	ds_read_b64_tr_b16 v[124:125], v240 offset:39424
	s_waitcnt lgkmcnt(10)
	v_mfma_f32_32x32x16_bf16 v[66:81], v[198:201], v[174:177], v[66:81]
	v_add_f32_e32 v233, v126, v233
	v_cvt_pk_bf16_f32 v168, v126, v127
	v_add_f32_e32 v233, v127, v233
	v_add_f32_e32 v233, v128, v233
	v_cvt_pk_bf16_f32 v169, v128, v129
	v_add_f32_e32 v233, v129, v233
	ds_read_b64_tr_b16 v[126:127], v240 offset:39936
	ds_read_b64_tr_b16 v[128:129], v240 offset:40448
	s_waitcnt lgkmcnt(11)
	v_mfma_f32_32x32x16_bf16 v[82:97], v[222:225], v[178:181], v[82:97]
	v_add_f32_e32 v233, v98, v233
	v_cvt_pk_bf16_f32 v186, v98, v99
	v_add_f32_e32 v233, v99, v233
	v_add_f32_e32 v233, v100, v233
	v_cvt_pk_bf16_f32 v187, v100, v101
	v_add_f32_e32 v233, v101, v233
	ds_read_b64_tr_b16 v[98:99], v240 offset:32768
	ds_read_b64_tr_b16 v[100:101], v240 offset:33280
	s_waitcnt lgkmcnt(12)
	v_mfma_f32_32x32x16_bf16 v[66:81], v[218:221], v[178:181], v[66:81]
	v_add_f32_e32 v233, v102, v233
	v_cvt_pk_bf16_f32 v188, v102, v103
	v_add_f32_e32 v233, v103, v233
	v_add_f32_e32 v233, v104, v233
	v_cvt_pk_bf16_f32 v189, v104, v105
	v_add_f32_e32 v233, v105, v233
	ds_read_b64_tr_b16 v[102:103], v240 offset:33792
	ds_read_b64_tr_b16 v[104:105], v240 offset:34304
	s_waitcnt lgkmcnt(13)
	v_mfma_f32_32x32x16_bf16 v[82:97], v[214:217], v[182:185], v[82:97]
	v_add_f32_e32 v233, v106, v233
	v_cvt_pk_bf16_f32 v190, v106, v107
	v_add_f32_e32 v233, v107, v233
	v_add_f32_e32 v233, v108, v233
	v_cvt_pk_bf16_f32 v191, v108, v109
	v_add_f32_e32 v233, v109, v233
	ds_read_b64_tr_b16 v[106:107], v240 offset:34816
	ds_read_b64_tr_b16 v[108:109], v240 offset:35328
	s_waitcnt lgkmcnt(14)
	v_mfma_f32_32x32x16_bf16 v[66:81], v[194:197], v[182:185], v[66:81]
	v_add_f32_e32 v233, v110, v233
	v_cvt_pk_bf16_f32 v192, v110, v111
	v_add_f32_e32 v233, v111, v233
	v_add_f32_e32 v233, v112, v233
	v_cvt_pk_bf16_f32 v193, v112, v113
	v_add_f32_e32 v233, v113, v233
	ds_read_b64_tr_b16 v[110:111], v240 offset:35840
	ds_read_b64_tr_b16 v[112:113], v240 offset:36352
	v_pk_add_f32 v[226:227], v[226:227], v[232:233]
	s_waitcnt lgkmcnt(6)
	v_mfma_f32_32x32x16_bf16 v[34:49], v[162:165], v[98:101], v[34:49]
	v_exp_f32_e32 v82, v82
	v_exp_f32_e32 v83, v83
	v_exp_f32_e32 v84, v84
	v_exp_f32_e32 v85, v85
	s_waitcnt lgkmcnt(6)
	v_mfma_f32_32x32x16_bf16 v[50:65], v[162:165], v[114:117], v[50:65]
	v_exp_f32_e32 v86, v86
	v_exp_f32_e32 v87, v87
	v_exp_f32_e32 v88, v88
	v_exp_f32_e32 v89, v89
	s_waitcnt lgkmcnt(4)
	v_mfma_f32_32x32x16_bf16 v[34:49], v[166:169], v[102:105], v[34:49]
	v_exp_f32_e32 v90, v90
	v_exp_f32_e32 v91, v91
	v_exp_f32_e32 v92, v92
	v_exp_f32_e32 v93, v93
	s_waitcnt lgkmcnt(4)
	v_mfma_f32_32x32x16_bf16 v[50:65], v[166:169], v[118:121], v[50:65]
	v_exp_f32_e32 v94, v94
	v_exp_f32_e32 v95, v95
	v_exp_f32_e32 v96, v96
	v_exp_f32_e32 v97, v97
	s_waitcnt lgkmcnt(2)
	v_mfma_f32_32x32x16_bf16 v[34:49], v[186:189], v[106:109], v[34:49]
	v_exp_f32_e32 v66, v66
	v_exp_f32_e32 v67, v67
	v_exp_f32_e32 v68, v68
	v_exp_f32_e32 v69, v69
	s_waitcnt lgkmcnt(2)
	v_mfma_f32_32x32x16_bf16 v[50:65], v[186:189], v[122:125], v[50:65]
	v_exp_f32_e32 v70, v70
	v_exp_f32_e32 v71, v71
	v_exp_f32_e32 v72, v72
	v_exp_f32_e32 v73, v73
	s_waitcnt lgkmcnt(0)
	v_mfma_f32_32x32x16_bf16 v[34:49], v[190:193], v[110:113], v[34:49]
	v_exp_f32_e32 v74, v74
	v_exp_f32_e32 v75, v75
	v_exp_f32_e32 v76, v76
	v_exp_f32_e32 v77, v77
	s_waitcnt lgkmcnt(0)
	v_mfma_f32_32x32x16_bf16 v[50:65], v[190:193], v[126:129], v[50:65]
	v_exp_f32_e32 v78, v78
	v_exp_f32_e32 v79, v79
	v_exp_f32_e32 v80, v80
	v_exp_f32_e32 v81, v81
	s_add_i32 s8, s14, 0x2000
	s_cmpk_lg_i32 s14, 0x6000
	s_cselect_b32 s14, s8, 0
	s_add_i32 s8, s16, 0x2000
	s_cmpk_lg_i32 s16, 0x6000
	s_cselect_b32 s16, s8, 0
	s_add_i32 s8, s15, 0x2000
	s_cmpk_lg_i32 s15, 0x6000
	s_cselect_b32 s15, s8, 0
	s_mov_b64 s[8:9], 0x4000
	v_lshl_add_u64 v[228:229], v[228:229], 0, s[8:9]
	s_cmpk_eq_i32 s13, 0x83
	v_lshl_add_u64 v[230:231], v[230:231], 0, s[8:9]
	s_cbranch_scc1 .LBB0_903
